# H2 segment-state combine loop software-pipelined (loads of next segment issued before fma of current), on v16
# speedup vs baseline: 1.0011x; 1.0011x over previous
.Lh2c_a:
	s_add_i32 s26, s26, -1
	s_add_i32 s20, s20, 8
	v_add_u32_e32 v50, 0x80, v50
	s_cmp_eq_u32 s26, 0
	s_cbranch_scc1 .Lh2c_a_last
	s_ashr_i32 s21, s20, 31
	s_lshl_b64 s[28:29], s[20:21], 13
	v_lshl_add_u64 v[234:235], v[78:79], 0, s[28:29]
	s_movk_i32 s21, 0x1000
	v_ashrrev_i32_e32 v51, 31, v50
	v_add_co_u32_e32 v236, vcc, s21, v234
	v_lshl_add_u64 v[238:239], v[50:51], 2, s[90:91]
	s_nop 0
	v_addc_co_u32_e32 v237, vcc, 0, v235, vcc
	global_load_dwordx4 v[198:201], v[234:235], off
	s_nop 0
	global_load_dwordx4 v[202:205], v[238:239], off
	s_nop 0
	global_load_dwordx4 v[206:209], v[234:235], off offset:1024
	global_load_dwordx4 v[210:213], v[234:235], off offset:2048
	global_load_dwordx4 v[214:217], v[234:235], off offset:3072
	s_nop 0
	global_load_dwordx4 v[218:221], v[236:237], off
	global_load_dwordx4 v[222:225], v[236:237], off offset:1024
	global_load_dwordx4 v[226:229], v[236:237], off offset:2048
	global_load_dwordx4 v[230:233], v[236:237], off offset:3072
	s_waitcnt vmcnt(9)
	v_pk_fma_f32 v[4:5], v[4:5], v[58:59], v[54:55]
	v_pk_fma_f32 v[2:3], v[2:3], v[56:57], v[52:53]
	v_pk_fma_f32 v[24:25], v[24:25], v[58:59], v[62:63]
	v_pk_fma_f32 v[22:23], v[22:23], v[56:57], v[60:61]
	v_pk_fma_f32 v[28:29], v[28:29], v[58:59], v[66:67]
	v_pk_fma_f32 v[26:27], v[26:27], v[56:57], v[64:65]
	v_pk_fma_f32 v[32:33], v[32:33], v[58:59], v[70:71]
	v_pk_fma_f32 v[30:31], v[30:31], v[56:57], v[68:69]
	v_pk_fma_f32 v[20:21], v[20:21], v[58:59], v[74:75]
	v_pk_fma_f32 v[18:19], v[18:19], v[56:57], v[72:73]
	v_pk_fma_f32 v[8:9], v[8:9], v[58:59], v[84:85]
	v_pk_fma_f32 v[6:7], v[6:7], v[56:57], v[82:83]
	v_pk_fma_f32 v[12:13], v[12:13], v[58:59], v[88:89]
	v_pk_fma_f32 v[10:11], v[10:11], v[56:57], v[86:87]
	v_pk_fma_f32 v[16:17], v[16:17], v[58:59], v[92:93]
	v_pk_fma_f32 v[14:15], v[14:15], v[56:57], v[90:91]
	s_add_i32 s26, s26, -1
	s_add_i32 s20, s20, 8
	v_add_u32_e32 v50, 0x80, v50
	s_cmp_eq_u32 s26, 0
	s_cbranch_scc1 .Lh2c_b_last
	s_ashr_i32 s21, s20, 31
	s_lshl_b64 s[28:29], s[20:21], 13
	v_lshl_add_u64 v[72:73], v[78:79], 0, s[28:29]
	s_movk_i32 s21, 0x1000
	v_ashrrev_i32_e32 v51, 31, v50
	v_add_co_u32_e32 v76, vcc, s21, v72
	v_lshl_add_u64 v[56:57], v[50:51], 2, s[90:91]
	s_nop 0
	v_addc_co_u32_e32 v77, vcc, 0, v73, vcc
	global_load_dwordx4 v[52:55], v[72:73], off
	s_nop 0
	global_load_dwordx4 v[56:59], v[56:57], off
	s_nop 0
	global_load_dwordx4 v[60:63], v[72:73], off offset:1024
	global_load_dwordx4 v[64:67], v[72:73], off offset:2048
	global_load_dwordx4 v[68:71], v[72:73], off offset:3072
	s_nop 0
	global_load_dwordx4 v[72:75], v[76:77], off
	global_load_dwordx4 v[82:85], v[76:77], off offset:1024
	global_load_dwordx4 v[86:89], v[76:77], off offset:2048
	global_load_dwordx4 v[90:93], v[76:77], off offset:3072
	s_waitcnt vmcnt(9)
	v_pk_fma_f32 v[4:5], v[4:5], v[204:205], v[200:201]
	v_pk_fma_f32 v[2:3], v[2:3], v[202:203], v[198:199]
	v_pk_fma_f32 v[24:25], v[24:25], v[204:205], v[208:209]
	v_pk_fma_f32 v[22:23], v[22:23], v[202:203], v[206:207]
	v_pk_fma_f32 v[28:29], v[28:29], v[204:205], v[212:213]
	v_pk_fma_f32 v[26:27], v[26:27], v[202:203], v[210:211]
	v_pk_fma_f32 v[32:33], v[32:33], v[204:205], v[216:217]
	v_pk_fma_f32 v[30:31], v[30:31], v[202:203], v[214:215]
	v_pk_fma_f32 v[20:21], v[20:21], v[204:205], v[220:221]
	v_pk_fma_f32 v[18:19], v[18:19], v[202:203], v[218:219]
	v_pk_fma_f32 v[8:9], v[8:9], v[204:205], v[224:225]
	v_pk_fma_f32 v[6:7], v[6:7], v[202:203], v[222:223]
	v_pk_fma_f32 v[12:13], v[12:13], v[204:205], v[228:229]
	v_pk_fma_f32 v[10:11], v[10:11], v[202:203], v[226:227]
	v_pk_fma_f32 v[16:17], v[16:17], v[204:205], v[232:233]
	v_pk_fma_f32 v[14:15], v[14:15], v[202:203], v[230:231]
	s_branch .Lh2c_a
.Lh2c_a_last:
	s_waitcnt vmcnt(0)
	v_pk_fma_f32 v[4:5], v[4:5], v[58:59], v[54:55]
	v_pk_fma_f32 v[2:3], v[2:3], v[56:57], v[52:53]
	v_pk_fma_f32 v[24:25], v[24:25], v[58:59], v[62:63]
	v_pk_fma_f32 v[22:23], v[22:23], v[56:57], v[60:61]
	v_pk_fma_f32 v[28:29], v[28:29], v[58:59], v[66:67]
	v_pk_fma_f32 v[26:27], v[26:27], v[56:57], v[64:65]
	v_pk_fma_f32 v[32:33], v[32:33], v[58:59], v[70:71]
	v_pk_fma_f32 v[30:31], v[30:31], v[56:57], v[68:69]
	v_pk_fma_f32 v[20:21], v[20:21], v[58:59], v[74:75]
	v_pk_fma_f32 v[18:19], v[18:19], v[56:57], v[72:73]
	v_pk_fma_f32 v[8:9], v[8:9], v[58:59], v[84:85]
	v_pk_fma_f32 v[6:7], v[6:7], v[56:57], v[82:83]
	v_pk_fma_f32 v[12:13], v[12:13], v[58:59], v[88:89]
	v_pk_fma_f32 v[10:11], v[10:11], v[56:57], v[86:87]
	v_pk_fma_f32 v[16:17], v[16:17], v[58:59], v[92:93]
	v_pk_fma_f32 v[14:15], v[14:15], v[56:57], v[90:91]
	s_branch .LBB0_386
.Lh2c_b_last:
	s_waitcnt vmcnt(0)
	v_pk_fma_f32 v[4:5], v[4:5], v[204:205], v[200:201]
	v_pk_fma_f32 v[2:3], v[2:3], v[202:203], v[198:199]
	v_pk_fma_f32 v[24:25], v[24:25], v[204:205], v[208:209]
	v_pk_fma_f32 v[22:23], v[22:23], v[202:203], v[206:207]
	v_pk_fma_f32 v[28:29], v[28:29], v[204:205], v[212:213]
	v_pk_fma_f32 v[26:27], v[26:27], v[202:203], v[210:211]
	v_pk_fma_f32 v[32:33], v[32:33], v[204:205], v[216:217]
	v_pk_fma_f32 v[30:31], v[30:31], v[202:203], v[214:215]
	v_pk_fma_f32 v[20:21], v[20:21], v[204:205], v[220:221]
	v_pk_fma_f32 v[18:19], v[18:19], v[202:203], v[218:219]
	v_pk_fma_f32 v[8:9], v[8:9], v[204:205], v[224:225]
	v_pk_fma_f32 v[6:7], v[6:7], v[202:203], v[222:223]
	v_pk_fma_f32 v[12:13], v[12:13], v[204:205], v[228:229]
	v_pk_fma_f32 v[10:11], v[10:11], v[202:203], v[226:227]
	v_pk_fma_f32 v[16:17], v[16:17], v[204:205], v[232:233]
	v_pk_fma_f32 v[14:15], v[14:15], v[202:203], v[230:231]
	s_branch .LBB0_386
